# code placement: 20 bytes of s_nop after the attention phase so the GEMM phases P4-P8 sit at the baseline's byte alignment (mod 64)
# baseline (speedup 1.0000x reference)
; #define SEAM(k) do { if (IN(k) && IN((k) + 1)) xcd_barrier(xbar); } while (0)
; __device__ __forceinline__ void xcd_barrier(const XcdBarrier& b) {
;     asm volatile("s_waitcnt vmcnt(0)" ::: "memory");
;     __syncthreads();
;     if (threadIdx.x == 0) {
;         unsigned* bar = b.bar;
;         __builtin_amdgcn_s_waitcnt(0);
;         unsigned nloc = b.st[0], nx = b.st[1];
;         if (nloc == 0u) { xcd_barrier_complete(bar, b.x, nloc, nx); b.st[0] = nloc; b.st[1] = nx; }
; __global__ void __launch_bounds__(512, 2) fwd_megakernel(Args args) {
;     ...
;     SEAM(3);
.LBB0_606:
	s_nop 0
	s_nop 0
	s_nop 0
	s_nop 0
	s_nop 0
	s_cmp_gt_i32 s31, 4
	s_cselect_b64 s[2:3], -1, 0
	s_and_b64 s[0:1], s[0:1], s[2:3]
	s_andn2_b64 vcc, exec, s[0:1]
	s_cbranch_vccnz .LBB0_660
	s_waitcnt vmcnt(0)
	s_waitcnt vmcnt(0) lgkmcnt(0)
	s_barrier
	s_and_saveexec_b64 s[0:1], s[82:83]
	s_cbranch_execz .LBB0_659
	s_add_i32 s4, 0, 0x22000
	v_mov_b32_e32 v0, s4
	s_waitcnt vmcnt(0) expcnt(0) lgkmcnt(0)
	ds_read_b32 v2, v0
	s_add_i32 s4, 0, 0x22004
	v_mov_b32_e32 v0, s4
	ds_read_b32 v0, v0
	s_waitcnt lgkmcnt(1)
	v_cmp_ne_u32_e32 vcc, 0, v2
	s_cbranch_vccnz .LBB0_623
	v_readlane_b32 s4, v254, 0
	s_mul_i32 s18, s93, s4
	s_add_u32 s4, s28, 0x1000
	s_addc_u32 s5, s29, 0
	s_add_u32 s6, s28, 0x1100
	s_addc_u32 s7, s29, 0
	s_add_u32 s8, s28, 0x1200
	s_addc_u32 s9, s29, 0
	s_add_u32 s10, s28, 0x1300
	s_mul_i32 s18, s18, s92
	s_addc_u32 s11, s29, 0
	s_mov_b32 s19, 1
	v_mov_b32_e32 v16, 0
	s_branch .LBB0_611
